# operand-stationary MFMA order in the diff attention loop and in the three GEMM K loops (144 adjacent independent MFMAs swapped so consecutive MFMAs share an input operand); bit-identical
# baseline (speedup 1.0000x reference)
; #define PG8_STAGE(bufoff, gbase, voff) do { _Pragma("unroll") for (int _i = 0; _i < 2; ++_i) \
;         __builtin_amdgcn_global_load_lds((const unsigned*)((const char*)(gbase) + (voff)[_i]), (PG8_LAS unsigned*)(lds + (bufoff) + ldsw + _i * 8192), 16, 0, 0); } while (0)
; #define PG8_LDA(dst, b, h) do { _Pragma("unroll") for (int m = 0; m < 4; ++m) _Pragma("unroll") for (int k = 0; k < 2; ++k) dst[m][k] = *(const PG8_LAS bf16x8*)(lds + PG8_SA(b, h) + aoff + m * 2048 + k * 1024); } while (0)
; #define PG8_LDB(dst, b, h) do { _Pragma("unroll") for (int n = 0; n < 2; ++n) _Pragma("unroll") for (int k = 0; k < 2; ++k) dst[n][k] = *(const PG8_LAS bf16x8*)(lds + PG8_SB(b, h) + boff + n * 2048 + k * 1024); } while (0)
; #define PG8_MMA(ai, bj, At, Bt) do { __builtin_amdgcn_s_setprio(1); _Pragma("unroll") for (int m = 0; m < 4; ++m) _Pragma("unroll") for (int n = 0; n < 2; ++n) _Pragma("unroll") for (int k = 0; k < 2; ++k) \
;         acc[ai][bj][m][n] = __builtin_amdgcn_mfma_f32_16x16x32_bf16(Bt[n][k], At[m][k], acc[ai][bj][m][n], 0, 0, 0); __builtin_amdgcn_s_setprio(0); } while (0)
; #define PG8_WAIT_V(n) asm volatile("s_waitcnt vmcnt(" #n ")" ::: "memory")
; #define PG8_BAR __builtin_amdgcn_s_barrier()
; template <class Epi, class Sched, bool ALIGN_EPI = false, bool SP2 = false>
; __device__ __forceinline__ void gemm_phase(PG8_LAS unsigned char* lds, const Gemm g, const Sched& S, const Epi& E) {
;     ...
;         for (int t = 0; t < nt; t += 2) {
;             const bool last = (t == nt - 2);
;             const char* a1 = cA + (size_t)(t + 1) * kstep;
;             const char* a2 = last ? nA : cA + (size_t)(t + 2) * kstep; const char* b2 = last ? nB : cB + (size_t)(t + 2) * kstep;
;             const char* a3 = a2 + kstep; const char* b3 = b2 + kstep;
;             if (last && has_next) S.a_ready(nxt);
;             if constexpr (SP2) {
;             PG8_LDB(B0, 0, 0); PG8_LDB(B1, 0, 1); PG8_SCHED; PG8_LDA(At, 0, 0); PG8_STAGE(PG8_SA(1, 1), a1 + hstep, voffA);
;             PG8_WAIT_V(8); PG8_WAIT_L(0); PG8_BAR; PG8_MMA(0, 0, At, B0); PG8_MMA(0, 1, At, B1); PG8_BAR; PG8_SCHED;
;             PG8_LDA(At, 0, 1); PG8_STAGE(PG8_SB(0, 0), b2, voffB); PG8_STAGE(PG8_SB(0, 1), b2 + hstep, voffB); PG8_STAGE(PG8_SA(0, 0), a2, voffA);
;             PG8_WAIT_V(8); PG8_WAIT_L(0); PG8_BAR; PG8_MMA(1, 0, At, B0); PG8_MMA(1, 1, At, B1); PG8_BAR; PG8_SCHED;
.LBB0_241:
	ds_read_b128 v[128:131], v207
	ds_read_b128 v[132:135], v207 offset:1024
	ds_read_b128 v[136:139], v207 offset:2048
	ds_read_b128 v[140:143], v207 offset:3072
	s_waitcnt vmcnt(0)
	ds_read_b128 v[144:147], v212
	ds_read_b128 v[148:151], v212 offset:1024
	ds_read_b128 v[152:155], v212 offset:2048
	ds_read_b128 v[156:159], v212 offset:3072
	s_add_u32 s10, s6, 0xfffc0080
	s_addc_u32 s11, s7, -1
	s_cmp_eq_u32 s85, 12
	s_cselect_b32 s15, s9, s11
	s_cselect_b32 s14, s77, s10
	s_cselect_b32 s11, s75, s83
	s_cselect_b32 s10, s84, s82
	v_lshl_add_u64 v[198:199], s[6:7], 0, v[184:185]
	s_add_i32 m0, s13, 0xc000
	ds_read_b128 v[194:197], v208
	ds_read_b128 v[216:219], v208 offset:1024
	ds_read_b128 v[220:223], v208 offset:2048
	ds_read_b128 v[224:227], v208 offset:3072
	ds_read_b128 v[228:231], v208 offset:4096
	ds_read_b128 v[232:235], v208 offset:5120
	ds_read_b128 v[236:239], v208 offset:6144
	ds_read_b128 v[240:243], v208 offset:7168
	global_load_lds_dwordx4 v[198:199], off
	v_lshl_add_u64 v[198:199], s[6:7], 0, v[186:187]
	s_add_i32 m0, s13, 0xe000
	s_nop 0
	global_load_lds_dwordx4 v[198:199], off
	s_waitcnt vmcnt(8)
	s_waitcnt lgkmcnt(0)
	s_barrier
	s_setprio 1
	s_waitcnt lgkmcnt(0)
	v_mfma_f32_16x16x32_bf16 v[120:123], v[128:131], v[194:197], v[120:123]
	v_mfma_f32_16x16x32_bf16 v[124:127], v[136:139], v[194:197], v[124:127]
	v_mfma_f32_16x16x32_bf16 v[108:111], v[136:139], v[220:223], v[108:111]
	v_mfma_f32_16x16x32_bf16 v[104:107], v[128:131], v[220:223], v[104:107]
	v_mfma_f32_16x16x32_bf16 v[88:91], v[128:131], v[228:231], v[88:91]
	v_mfma_f32_16x16x32_bf16 v[92:95], v[136:139], v[228:231], v[92:95]
	v_mfma_f32_16x16x32_bf16 v[76:79], v[136:139], v[236:239], v[76:79]
	v_mfma_f32_16x16x32_bf16 v[72:75], v[128:131], v[236:239], v[72:75]
	v_mfma_f32_16x16x32_bf16 v[120:123], v[132:135], v[216:219], v[120:123]
	v_mfma_f32_16x16x32_bf16 v[124:127], v[140:143], v[216:219], v[124:127]
	v_mfma_f32_16x16x32_bf16 v[108:111], v[140:143], v[224:227], v[108:111]
	v_mfma_f32_16x16x32_bf16 v[104:107], v[132:135], v[224:227], v[104:107]
	v_mfma_f32_16x16x32_bf16 v[88:91], v[132:135], v[232:235], v[88:91]
	v_mfma_f32_16x16x32_bf16 v[92:95], v[140:143], v[232:235], v[92:95]
	v_mfma_f32_16x16x32_bf16 v[76:79], v[140:143], v[240:243], v[76:79]
	v_mfma_f32_16x16x32_bf16 v[72:75], v[132:135], v[240:243], v[72:75]
	s_setprio 0
	s_setprio 1
	v_mfma_f32_16x16x32_bf16 v[112:115], v[144:147], v[194:197], v[112:115]
	v_mfma_f32_16x16x32_bf16 v[116:119], v[152:155], v[194:197], v[116:119]
	v_mfma_f32_16x16x32_bf16 v[100:103], v[152:155], v[220:223], v[100:103]
	v_mfma_f32_16x16x32_bf16 v[96:99], v[144:147], v[220:223], v[96:99]
	v_mfma_f32_16x16x32_bf16 v[80:83], v[144:147], v[228:231], v[80:83]
	v_mfma_f32_16x16x32_bf16 v[84:87], v[152:155], v[228:231], v[84:87]
	v_mfma_f32_16x16x32_bf16 v[68:71], v[152:155], v[236:239], v[68:71]
	v_mfma_f32_16x16x32_bf16 v[64:67], v[144:147], v[236:239], v[64:67]
	v_mfma_f32_16x16x32_bf16 v[112:115], v[148:151], v[216:219], v[112:115]
	v_mfma_f32_16x16x32_bf16 v[116:119], v[156:159], v[216:219], v[116:119]
	v_mfma_f32_16x16x32_bf16 v[100:103], v[156:159], v[224:227], v[100:103]
	v_mfma_f32_16x16x32_bf16 v[96:99], v[148:151], v[224:227], v[96:99]
	v_mfma_f32_16x16x32_bf16 v[80:83], v[148:151], v[232:235], v[80:83]
	v_mfma_f32_16x16x32_bf16 v[84:87], v[156:159], v[232:235], v[84:87]
	v_mfma_f32_16x16x32_bf16 v[68:71], v[156:159], v[240:243], v[68:71]
	v_mfma_f32_16x16x32_bf16 v[64:67], v[148:151], v[240:243], v[64:67]
	s_setprio 0
	s_barrier
	s_add_i32 s87, s63, s12
	v_lshl_add_u64 v[198:199], s[10:11], 0, v[162:163]
	s_mov_b32 m0, s87
	ds_read_b128 v[194:197], v208 offset:16384
	ds_read_b128 v[216:219], v208 offset:17408
	ds_read_b128 v[220:223], v208 offset:18432
	ds_read_b128 v[224:227], v208 offset:19456
	ds_read_b128 v[228:231], v208 offset:20480
	ds_read_b128 v[232:235], v208 offset:21504
	ds_read_b128 v[236:239], v208 offset:22528
	ds_read_b128 v[240:243], v208 offset:23552
	global_load_lds_dwordx4 v[198:199], off
	s_add_i32 m0, s87, 0x2000
	s_add_u32 s88, s10, 0x40000
	v_lshl_add_u64 v[244:245], s[10:11], 0, v[166:167]
	s_addc_u32 s89, s11, 0
	s_add_i32 s87, s68, s12
	global_load_lds_dwordx4 v[244:245], off
	v_lshl_add_u64 v[246:247], s[88:89], 0, v[162:163]
	s_mov_b32 m0, s87
	v_lshl_add_u64 v[248:249], s[14:15], 0, v[164:165]
	global_load_lds_dwordx4 v[246:247], off
	v_lshl_add_u64 v[246:247], s[88:89], 0, v[166:167]
	s_add_i32 m0, s87, 0x2000
	s_nop 0
	global_load_lds_dwordx4 v[246:247], off
	v_lshl_add_u64 v[246:247], s[14:15], 0, v[160:161]
	s_mov_b32 m0, s13
	s_nop 0
	global_load_lds_dwordx4 v[246:247], off
	s_mov_b32 m0, s66
	s_nop 0
	global_load_lds_dwordx4 v[248:249], off
	s_waitcnt vmcnt(8)
	s_waitcnt lgkmcnt(0)
	s_barrier
; #define PG8_STAGE(bufoff, gbase, voff) do { _Pragma("unroll") for (int _i = 0; _i < 2; ++_i) \
;         __builtin_amdgcn_global_load_lds((const unsigned*)((const char*)(gbase) + (voff)[_i]), (PG8_LAS unsigned*)(lds + (bufoff) + ldsw + _i * 8192), 16, 0, 0); } while (0)
; #define PG8_LDA(dst, b, h) do { _Pragma("unroll") for (int m = 0; m < 4; ++m) _Pragma("unroll") for (int k = 0; k < 2; ++k) dst[m][k] = *(const PG8_LAS bf16x8*)(lds + PG8_SA(b, h) + aoff + m * 2048 + k * 1024); } while (0)
; #define PG8_LDB(dst, b, h) do { _Pragma("unroll") for (int n = 0; n < 2; ++n) _Pragma("unroll") for (int k = 0; k < 2; ++k) dst[n][k] = *(const PG8_LAS bf16x8*)(lds + PG8_SB(b, h) + boff + n * 2048 + k * 1024); } while (0)
; #define PG8_MMA(ai, bj, At, Bt) do { __builtin_amdgcn_s_setprio(1); _Pragma("unroll") for (int m = 0; m < 4; ++m) _Pragma("unroll") for (int n = 0; n < 2; ++n) _Pragma("unroll") for (int k = 0; k < 2; ++k) \
;         acc[ai][bj][m][n] = __builtin_amdgcn_mfma_f32_16x16x32_bf16(Bt[n][k], At[m][k], acc[ai][bj][m][n], 0, 0, 0); __builtin_amdgcn_s_setprio(0); } while (0)
; #define PG8_WAIT_V(n) asm volatile("s_waitcnt vmcnt(" #n ")" ::: "memory")
; #define PG8_WAIT_L(n) asm volatile("s_waitcnt lgkmcnt(" #n ")" ::: "memory")
; #define PG8_BAR __builtin_amdgcn_s_barrier()
; #define PG8_SCHED __builtin_amdgcn_sched_barrier(0)
; template <class Epi, class Sched, bool ALIGN_EPI = false, bool SP2 = false>
; __device__ __forceinline__ void gemm_phase(PG8_LAS unsigned char* lds, const Gemm g, const Sched& S, const Epi& E) {
;     ...
;             PG8_WAIT_V(8); PG8_WAIT_L(0); PG8_BAR; PG8_MMA(1, 0, At, B0); PG8_MMA(1, 1, At, B1); PG8_BAR; PG8_SCHED;
;             PG8_LDB(B0, 1, 0); PG8_LDB(B1, 1, 1); PG8_SCHED; PG8_LDA(At, 1, 0); PG8_STAGE(PG8_SA(0, 1), a2 + hstep, voffA);
;             PG8_WAIT_V(8); PG8_WAIT_L(0); PG8_BAR; PG8_MMA(0, 0, At, B0); PG8_MMA(0, 1, At, B1); PG8_BAR; PG8_SCHED;
	s_setprio 1
	s_waitcnt lgkmcnt(0)
	v_mfma_f32_16x16x32_bf16 v[56:59], v[128:131], v[194:197], v[56:59]
	v_mfma_f32_16x16x32_bf16 v[60:63], v[136:139], v[194:197], v[60:63]
	v_mfma_f32_16x16x32_bf16 v[44:47], v[136:139], v[220:223], v[44:47]
	v_mfma_f32_16x16x32_bf16 v[40:43], v[128:131], v[220:223], v[40:43]
	v_mfma_f32_16x16x32_bf16 v[24:27], v[128:131], v[228:231], v[24:27]
	v_mfma_f32_16x16x32_bf16 v[28:31], v[136:139], v[228:231], v[28:31]
	v_mfma_f32_16x16x32_bf16 v[12:15], v[136:139], v[236:239], v[12:15]
	v_mfma_f32_16x16x32_bf16 v[8:11], v[128:131], v[236:239], v[8:11]
	v_mfma_f32_16x16x32_bf16 v[56:59], v[132:135], v[216:219], v[56:59]
	v_mfma_f32_16x16x32_bf16 v[60:63], v[140:143], v[216:219], v[60:63]
	v_mfma_f32_16x16x32_bf16 v[44:47], v[140:143], v[224:227], v[44:47]
	v_mfma_f32_16x16x32_bf16 v[40:43], v[132:135], v[224:227], v[40:43]
	v_mfma_f32_16x16x32_bf16 v[24:27], v[132:135], v[232:235], v[24:27]
	v_mfma_f32_16x16x32_bf16 v[28:31], v[140:143], v[232:235], v[28:31]
	v_mfma_f32_16x16x32_bf16 v[12:15], v[140:143], v[240:243], v[12:15]
	v_mfma_f32_16x16x32_bf16 v[8:11], v[132:135], v[240:243], v[8:11]
	s_setprio 0
	s_setprio 1
	v_mfma_f32_16x16x32_bf16 v[48:51], v[144:147], v[194:197], v[48:51]
	v_mfma_f32_16x16x32_bf16 v[52:55], v[152:155], v[194:197], v[52:55]
	v_mfma_f32_16x16x32_bf16 v[36:39], v[152:155], v[220:223], v[36:39]
	v_mfma_f32_16x16x32_bf16 v[32:35], v[144:147], v[220:223], v[32:35]
	v_mfma_f32_16x16x32_bf16 v[16:19], v[144:147], v[228:231], v[16:19]
	v_mfma_f32_16x16x32_bf16 v[20:23], v[152:155], v[228:231], v[20:23]
	v_mfma_f32_16x16x32_bf16 v[4:7], v[152:155], v[236:239], v[4:7]
	v_mfma_f32_16x16x32_bf16 v[0:3], v[144:147], v[236:239], v[0:3]
	v_mfma_f32_16x16x32_bf16 v[48:51], v[148:151], v[216:219], v[48:51]
	v_mfma_f32_16x16x32_bf16 v[52:55], v[156:159], v[216:219], v[52:55]
	v_mfma_f32_16x16x32_bf16 v[36:39], v[156:159], v[224:227], v[36:39]
	v_mfma_f32_16x16x32_bf16 v[32:35], v[148:151], v[224:227], v[32:35]
	v_mfma_f32_16x16x32_bf16 v[16:19], v[148:151], v[232:235], v[16:19]
	v_mfma_f32_16x16x32_bf16 v[20:23], v[156:159], v[232:235], v[20:23]
	v_mfma_f32_16x16x32_bf16 v[4:7], v[156:159], v[240:243], v[4:7]
	v_mfma_f32_16x16x32_bf16 v[0:3], v[148:151], v[240:243], v[0:3]
	s_setprio 0
	s_barrier
	s_add_i32 s87, 0, 0x18000
	s_add_i32 s88, 0, 0x1c000
	v_add_u32_e32 v140, s87, v181
	v_add_u32_e32 v156, s88, v181
	ds_read_b128 v[128:131], v140
	ds_read_b128 v[132:135], v140 offset:1024
	ds_read_b128 v[136:139], v140 offset:2048
	ds_read_b128 v[140:143], v140 offset:3072
	ds_read_b128 v[144:147], v156
	ds_read_b128 v[148:151], v156 offset:1024
	ds_read_b128 v[152:155], v156 offset:2048
	ds_read_b128 v[156:159], v156 offset:3072
	s_add_u32 s14, s14, 0x40000
	s_addc_u32 s15, s15, 0
	s_mov_b32 m0, s67
	v_lshl_add_u64 v[250:251], s[14:15], 0, v[160:161]
	ds_read_b128 v[194:197], v208 offset:32768
	ds_read_b128 v[216:219], v208 offset:33792
	ds_read_b128 v[220:223], v208 offset:34816
	ds_read_b128 v[224:227], v208 offset:35840
	ds_read_b128 v[228:231], v208 offset:36864
	ds_read_b128 v[232:235], v208 offset:37888
	ds_read_b128 v[236:239], v208 offset:38912
	ds_read_b128 v[240:243], v208 offset:39936
	global_load_lds_dwordx4 v[250:251], off
	v_lshl_add_u64 v[250:251], s[14:15], 0, v[164:165]
	s_mov_b32 m0, s33
	s_nop 0
	global_load_lds_dwordx4 v[250:251], off
	s_waitcnt vmcnt(8)
	s_waitcnt lgkmcnt(0)
	s_barrier
	s_setprio 1
	s_waitcnt lgkmcnt(0)
	v_mfma_f32_16x16x32_bf16 v[120:123], v[128:131], v[194:197], v[120:123]
	v_mfma_f32_16x16x32_bf16 v[124:127], v[136:139], v[194:197], v[124:127]
	v_mfma_f32_16x16x32_bf16 v[108:111], v[136:139], v[220:223], v[108:111]
	v_mfma_f32_16x16x32_bf16 v[104:107], v[128:131], v[220:223], v[104:107]
	v_mfma_f32_16x16x32_bf16 v[88:91], v[128:131], v[228:231], v[88:91]
	v_mfma_f32_16x16x32_bf16 v[92:95], v[136:139], v[228:231], v[92:95]
	v_mfma_f32_16x16x32_bf16 v[76:79], v[136:139], v[236:239], v[76:79]
	v_mfma_f32_16x16x32_bf16 v[72:75], v[128:131], v[236:239], v[72:75]
	v_mfma_f32_16x16x32_bf16 v[120:123], v[132:135], v[216:219], v[120:123]
	v_mfma_f32_16x16x32_bf16 v[124:127], v[140:143], v[216:219], v[124:127]
	v_mfma_f32_16x16x32_bf16 v[108:111], v[140:143], v[224:227], v[108:111]
	v_mfma_f32_16x16x32_bf16 v[104:107], v[132:135], v[224:227], v[104:107]
	v_mfma_f32_16x16x32_bf16 v[88:91], v[132:135], v[232:235], v[88:91]
	v_mfma_f32_16x16x32_bf16 v[92:95], v[140:143], v[232:235], v[92:95]
	v_mfma_f32_16x16x32_bf16 v[76:79], v[140:143], v[240:243], v[76:79]
	v_mfma_f32_16x16x32_bf16 v[72:75], v[132:135], v[240:243], v[72:75]
	s_setprio 0
	s_setprio 1
	v_mfma_f32_16x16x32_bf16 v[112:115], v[144:147], v[194:197], v[112:115]
	v_mfma_f32_16x16x32_bf16 v[116:119], v[152:155], v[194:197], v[116:119]
	v_mfma_f32_16x16x32_bf16 v[100:103], v[152:155], v[220:223], v[100:103]
	v_mfma_f32_16x16x32_bf16 v[96:99], v[144:147], v[220:223], v[96:99]
	v_mfma_f32_16x16x32_bf16 v[80:83], v[144:147], v[228:231], v[80:83]
	v_mfma_f32_16x16x32_bf16 v[84:87], v[152:155], v[228:231], v[84:87]
	v_mfma_f32_16x16x32_bf16 v[68:71], v[152:155], v[236:239], v[68:71]
	v_mfma_f32_16x16x32_bf16 v[64:67], v[144:147], v[236:239], v[64:67]
	v_mfma_f32_16x16x32_bf16 v[112:115], v[148:151], v[216:219], v[112:115]
	v_mfma_f32_16x16x32_bf16 v[116:119], v[156:159], v[216:219], v[116:119]
	v_mfma_f32_16x16x32_bf16 v[100:103], v[156:159], v[224:227], v[100:103]
	v_mfma_f32_16x16x32_bf16 v[96:99], v[148:151], v[224:227], v[96:99]
	v_mfma_f32_16x16x32_bf16 v[80:83], v[148:151], v[232:235], v[80:83]
	v_mfma_f32_16x16x32_bf16 v[84:87], v[156:159], v[232:235], v[84:87]
	v_mfma_f32_16x16x32_bf16 v[68:71], v[156:159], v[240:243], v[68:71]
	v_mfma_f32_16x16x32_bf16 v[64:67], v[148:151], v[240:243], v[64:67]
	s_setprio 0
	s_barrier
; #define PG8_STAGE(bufoff, gbase, voff) do { _Pragma("unroll") for (int _i = 0; _i < 2; ++_i) \
;         __builtin_amdgcn_global_load_lds((const unsigned*)((const char*)(gbase) + (voff)[_i]), (PG8_LAS unsigned*)(lds + (bufoff) + ldsw + _i * 8192), 16, 0, 0); } while (0)
; #define PG8_LDA(dst, b, h) do { _Pragma("unroll") for (int m = 0; m < 4; ++m) _Pragma("unroll") for (int k = 0; k < 2; ++k) dst[m][k] = *(const PG8_LAS bf16x8*)(lds + PG8_SA(b, h) + aoff + m * 2048 + k * 1024); } while (0)
; #define PG8_MMA(ai, bj, At, Bt) do { __builtin_amdgcn_s_setprio(1); _Pragma("unroll") for (int m = 0; m < 4; ++m) _Pragma("unroll") for (int n = 0; n < 2; ++n) _Pragma("unroll") for (int k = 0; k < 2; ++k) \
;         acc[ai][bj][m][n] = __builtin_amdgcn_mfma_f32_16x16x32_bf16(Bt[n][k], At[m][k], acc[ai][bj][m][n], 0, 0, 0); __builtin_amdgcn_s_setprio(0); } while (0)
; #define PG8_WAIT_V(n) asm volatile("s_waitcnt vmcnt(" #n ")" ::: "memory")
; #define PG8_WAIT_L(n) asm volatile("s_waitcnt lgkmcnt(" #n ")" ::: "memory")
; #define PG8_BAR __builtin_amdgcn_s_barrier()
; #define PG8_SCHED __builtin_amdgcn_sched_barrier(0)
; template <class Epi, class Sched, bool ALIGN_EPI = false, bool SP2 = false>
; __device__ __forceinline__ void gemm_phase(PG8_LAS unsigned char* lds, const Gemm g, const Sched& S, const Epi& E) {
;     ...
;         for (int t = 0; t < nt; t += 2) {
;     ...
;             PG8_LDA(At, 1, 1); PG8_STAGE(PG8_SB(1, 0), b3, voffB); PG8_STAGE(PG8_SB(1, 1), b3 + hstep, voffB); PG8_STAGE(PG8_SA(1, 0), a3, voffA);
;             PG8_WAIT_V(8); PG8_WAIT_L(0); PG8_BAR; PG8_MMA(1, 0, At, B0); PG8_MMA(1, 1, At, B1); PG8_BAR; PG8_SCHED;
;     ...
;         if constexpr (ALIGN_EPI) { if (wr == 0) PG8_BAR; }
	s_add_i32 s14, s87, s12
	v_lshl_add_u64 v[198:199], v[198:199], 0, s[44:45]
	s_mov_b32 m0, s14
	ds_read_b128 v[194:197], v208 offset:49152
	ds_read_b128 v[216:219], v208 offset:50176
	ds_read_b128 v[220:223], v208 offset:51200
	ds_read_b128 v[224:227], v208 offset:52224
	ds_read_b128 v[228:231], v208 offset:53248
	ds_read_b128 v[232:235], v208 offset:54272
	ds_read_b128 v[236:239], v208 offset:55296
	ds_read_b128 v[240:243], v208 offset:56320
	global_load_lds_dwordx4 v[198:199], off
	s_add_i32 m0, s14, 0x2000
	s_add_u32 s10, s10, 0x40080
	v_lshl_add_u64 v[198:199], v[244:245], 0, s[44:45]
	s_addc_u32 s11, s11, 0
	s_add_i32 s14, s88, s12
	global_load_lds_dwordx4 v[198:199], off
	v_lshl_add_u64 v[198:199], s[10:11], 0, v[162:163]
	s_mov_b32 m0, s14
	s_nop 0
	global_load_lds_dwordx4 v[198:199], off
	v_lshl_add_u64 v[198:199], s[10:11], 0, v[166:167]
	s_add_i32 m0, s14, 0x2000
	s_nop 0
	global_load_lds_dwordx4 v[198:199], off
	v_lshl_add_u64 v[198:199], v[246:247], 0, s[44:45]
	s_mov_b32 m0, s52
	s_nop 0
	global_load_lds_dwordx4 v[198:199], off
	v_lshl_add_u64 v[198:199], v[248:249], 0, s[44:45]
	s_mov_b32 m0, s53
	s_nop 0
	global_load_lds_dwordx4 v[198:199], off
	s_waitcnt vmcnt(8)
	s_waitcnt lgkmcnt(0)
	s_barrier
	s_setprio 1
	s_waitcnt lgkmcnt(0)
	v_mfma_f32_16x16x32_bf16 v[56:59], v[128:131], v[194:197], v[56:59]
	v_mfma_f32_16x16x32_bf16 v[60:63], v[136:139], v[194:197], v[60:63]
	v_mfma_f32_16x16x32_bf16 v[44:47], v[136:139], v[220:223], v[44:47]
	v_mfma_f32_16x16x32_bf16 v[40:43], v[128:131], v[220:223], v[40:43]
	v_mfma_f32_16x16x32_bf16 v[24:27], v[128:131], v[228:231], v[24:27]
	v_mfma_f32_16x16x32_bf16 v[28:31], v[136:139], v[228:231], v[28:31]
	v_mfma_f32_16x16x32_bf16 v[12:15], v[136:139], v[236:239], v[12:15]
	v_mfma_f32_16x16x32_bf16 v[8:11], v[128:131], v[236:239], v[8:11]
	v_mfma_f32_16x16x32_bf16 v[56:59], v[132:135], v[216:219], v[56:59]
	v_mfma_f32_16x16x32_bf16 v[60:63], v[140:143], v[216:219], v[60:63]
	v_mfma_f32_16x16x32_bf16 v[44:47], v[140:143], v[224:227], v[44:47]
	v_mfma_f32_16x16x32_bf16 v[40:43], v[132:135], v[224:227], v[40:43]
	v_mfma_f32_16x16x32_bf16 v[24:27], v[132:135], v[232:235], v[24:27]
	v_mfma_f32_16x16x32_bf16 v[28:31], v[140:143], v[232:235], v[28:31]
	v_mfma_f32_16x16x32_bf16 v[12:15], v[140:143], v[240:243], v[12:15]
	v_mfma_f32_16x16x32_bf16 v[8:11], v[132:135], v[240:243], v[8:11]
	s_setprio 0
	s_setprio 1
	v_mfma_f32_16x16x32_bf16 v[48:51], v[144:147], v[194:197], v[48:51]
	v_mfma_f32_16x16x32_bf16 v[52:55], v[152:155], v[194:197], v[52:55]
	v_mfma_f32_16x16x32_bf16 v[36:39], v[152:155], v[220:223], v[36:39]
	v_mfma_f32_16x16x32_bf16 v[32:35], v[144:147], v[220:223], v[32:35]
	v_mfma_f32_16x16x32_bf16 v[16:19], v[144:147], v[228:231], v[16:19]
	v_mfma_f32_16x16x32_bf16 v[20:23], v[152:155], v[228:231], v[20:23]
	v_mfma_f32_16x16x32_bf16 v[4:7], v[152:155], v[236:239], v[4:7]
	v_mfma_f32_16x16x32_bf16 v[0:3], v[144:147], v[236:239], v[0:3]
	v_mfma_f32_16x16x32_bf16 v[48:51], v[148:151], v[216:219], v[48:51]
	v_mfma_f32_16x16x32_bf16 v[52:55], v[156:159], v[216:219], v[52:55]
	v_mfma_f32_16x16x32_bf16 v[36:39], v[156:159], v[224:227], v[36:39]
	v_mfma_f32_16x16x32_bf16 v[32:35], v[148:151], v[224:227], v[32:35]
	v_mfma_f32_16x16x32_bf16 v[16:19], v[148:151], v[232:235], v[16:19]
	v_mfma_f32_16x16x32_bf16 v[20:23], v[156:159], v[232:235], v[20:23]
	v_mfma_f32_16x16x32_bf16 v[4:7], v[156:159], v[240:243], v[4:7]
	v_mfma_f32_16x16x32_bf16 v[0:3], v[148:151], v[240:243], v[0:3]
	s_setprio 0
	s_barrier
	s_add_i32 s85, s85, 2
	s_add_u32 s6, s6, 0x100
	s_addc_u32 s7, s7, 0
	s_add_u32 s82, s82, 0x100
	s_addc_u32 s83, s83, 0
	s_cmp_gt_u32 s85, 13
	s_cbranch_scc0 .LBB0_241
	s_and_b64 vcc, exec, s[46:47]
	s_cbranch_vccz .LBB0_244
	s_barrier

; #define PG8_STAGE(bufoff, gbase, voff) do { _Pragma("unroll") for (int _i = 0; _i < 2; ++_i) \
;         __builtin_amdgcn_global_load_lds((const unsigned*)((const char*)(gbase) + (voff)[_i]), (PG8_LAS unsigned*)(lds + (bufoff) + ldsw + _i * 8192), 16, 0, 0); } while (0)
; #define PG8_LDA(dst, b, h) do { _Pragma("unroll") for (int m = 0; m < 4; ++m) _Pragma("unroll") for (int k = 0; k < 2; ++k) dst[m][k] = *(const PG8_LAS bf16x8*)(lds + PG8_SA(b, h) + aoff + m * 2048 + k * 1024); } while (0)
; #define PG8_LDB(dst, b, h) do { _Pragma("unroll") for (int n = 0; n < 2; ++n) _Pragma("unroll") for (int k = 0; k < 2; ++k) dst[n][k] = *(const PG8_LAS bf16x8*)(lds + PG8_SB(b, h) + boff + n * 2048 + k * 1024); } while (0)
; #define PG8_MMA(ai, bj, At, Bt) do { __builtin_amdgcn_s_setprio(1); _Pragma("unroll") for (int m = 0; m < 4; ++m) _Pragma("unroll") for (int n = 0; n < 2; ++n) _Pragma("unroll") for (int k = 0; k < 2; ++k) \
;         acc[ai][bj][m][n] = __builtin_amdgcn_mfma_f32_16x16x32_bf16(Bt[n][k], At[m][k], acc[ai][bj][m][n], 0, 0, 0); __builtin_amdgcn_s_setprio(0); } while (0)
; #define PG8_WAIT_V(n) asm volatile("s_waitcnt vmcnt(" #n ")" ::: "memory")
; #define PG8_BAR __builtin_amdgcn_s_barrier()
; template <class Epi, class Sched, bool ALIGN_EPI = false, bool SP2 = false>
; __device__ __forceinline__ void gemm_phase(PG8_LAS unsigned char* lds, const Gemm g, const Sched& S, const Epi& E) {
;     ...
;         for (int t = 0; t < nt; t += 2) {
;             const bool last = (t == nt - 2);
;             const char* a1 = cA + (size_t)(t + 1) * kstep;
;             const char* a2 = last ? nA : cA + (size_t)(t + 2) * kstep; const char* b2 = last ? nB : cB + (size_t)(t + 2) * kstep;
;             const char* a3 = a2 + kstep; const char* b3 = b2 + kstep;
;             if (last && has_next) S.a_ready(nxt);
;             if constexpr (SP2) {
;             PG8_LDB(B0, 0, 0); PG8_LDB(B1, 0, 1); PG8_SCHED; PG8_LDA(At, 0, 0); PG8_STAGE(PG8_SA(1, 1), a1 + hstep, voffA);
;             PG8_WAIT_V(8); PG8_WAIT_L(0); PG8_BAR; PG8_MMA(0, 0, At, B0); PG8_MMA(0, 1, At, B1); PG8_BAR; PG8_SCHED;
;             PG8_LDA(At, 0, 1); PG8_STAGE(PG8_SB(0, 0), b2, voffB); PG8_STAGE(PG8_SB(0, 1), b2 + hstep, voffB); PG8_STAGE(PG8_SA(0, 0), a2, voffA);
;             PG8_WAIT_V(8); PG8_WAIT_L(0); PG8_BAR; PG8_MMA(1, 0, At, B0); PG8_MMA(1, 1, At, B1); PG8_BAR; PG8_SCHED;
.LBB0_513:
	ds_read_b128 v[144:147], v153
	ds_read_b128 v[156:159], v153 offset:1024
	ds_read_b128 v[160:163], v153 offset:2048
	ds_read_b128 v[164:167], v153 offset:3072
	ds_read_b128 v[168:171], v154
	ds_read_b128 v[172:175], v154 offset:1024
	ds_read_b128 v[176:179], v154 offset:2048
	ds_read_b128 v[182:185], v154 offset:3072
	s_add_u32 s30, s28, 0xfffc0080
	s_addc_u32 s31, s29, -1
	s_cmp_eq_u32 s53, 12
	s_cselect_b32 s37, s15, s31
	s_cselect_b32 s36, s49, s30
	s_cselect_b32 s31, s11, s52
	s_cselect_b32 s30, s50, s51
	v_lshl_add_u64 v[148:149], s[28:29], 0, v[136:137]
	s_add_i32 m0, s27, 0xc000
	ds_read_b128 v[186:189], v155
	ds_read_b128 v[194:197], v155 offset:1024
	ds_read_b128 v[198:201], v155 offset:2048
	ds_read_b128 v[202:205], v155 offset:3072
	ds_read_b128 v[206:209], v155 offset:4096
	ds_read_b128 v[210:213], v155 offset:5120
	ds_read_b128 v[214:217], v155 offset:6144
	ds_read_b128 v[218:221], v155 offset:7168
	global_load_lds_dwordx4 v[148:149], off
	v_lshl_add_u64 v[148:149], s[28:29], 0, v[138:139]
	s_add_i32 m0, s27, 0xe000
	s_nop 0
	global_load_lds_dwordx4 v[148:149], off
	s_waitcnt vmcnt(8)
	s_waitcnt lgkmcnt(0)
	s_barrier
	s_setprio 1
	s_waitcnt lgkmcnt(0)
	v_mfma_f32_16x16x32_bf16 v[124:127], v[144:147], v[186:189], v[124:127]
	v_mfma_f32_16x16x32_bf16 v[120:123], v[160:163], v[186:189], v[120:123]
	v_mfma_f32_16x16x32_bf16 v[104:107], v[160:163], v[198:201], v[104:107]
	v_mfma_f32_16x16x32_bf16 v[108:111], v[144:147], v[198:201], v[108:111]
	v_mfma_f32_16x16x32_bf16 v[92:95], v[144:147], v[206:209], v[92:95]
	v_mfma_f32_16x16x32_bf16 v[88:91], v[160:163], v[206:209], v[88:91]
	v_mfma_f32_16x16x32_bf16 v[72:75], v[160:163], v[214:217], v[72:75]
	v_mfma_f32_16x16x32_bf16 v[76:79], v[144:147], v[214:217], v[76:79]
	v_mfma_f32_16x16x32_bf16 v[124:127], v[156:159], v[194:197], v[124:127]
	v_mfma_f32_16x16x32_bf16 v[120:123], v[164:167], v[194:197], v[120:123]
	v_mfma_f32_16x16x32_bf16 v[104:107], v[164:167], v[202:205], v[104:107]
	v_mfma_f32_16x16x32_bf16 v[108:111], v[156:159], v[202:205], v[108:111]
	v_mfma_f32_16x16x32_bf16 v[92:95], v[156:159], v[210:213], v[92:95]
	v_mfma_f32_16x16x32_bf16 v[88:91], v[164:167], v[210:213], v[88:91]
	v_mfma_f32_16x16x32_bf16 v[72:75], v[164:167], v[218:221], v[72:75]
	v_mfma_f32_16x16x32_bf16 v[76:79], v[156:159], v[218:221], v[76:79]
	s_setprio 0
	s_setprio 1
	v_mfma_f32_16x16x32_bf16 v[116:119], v[168:171], v[186:189], v[116:119]
	v_mfma_f32_16x16x32_bf16 v[112:115], v[176:179], v[186:189], v[112:115]
	v_mfma_f32_16x16x32_bf16 v[96:99], v[176:179], v[198:201], v[96:99]
	v_mfma_f32_16x16x32_bf16 v[100:103], v[168:171], v[198:201], v[100:103]
	v_mfma_f32_16x16x32_bf16 v[84:87], v[168:171], v[206:209], v[84:87]
	v_mfma_f32_16x16x32_bf16 v[80:83], v[176:179], v[206:209], v[80:83]
	v_mfma_f32_16x16x32_bf16 v[64:67], v[176:179], v[214:217], v[64:67]
	v_mfma_f32_16x16x32_bf16 v[68:71], v[168:171], v[214:217], v[68:71]
	v_mfma_f32_16x16x32_bf16 v[116:119], v[172:175], v[194:197], v[116:119]
	v_mfma_f32_16x16x32_bf16 v[112:115], v[182:185], v[194:197], v[112:115]
	v_mfma_f32_16x16x32_bf16 v[96:99], v[182:185], v[202:205], v[96:99]
	v_mfma_f32_16x16x32_bf16 v[100:103], v[172:175], v[202:205], v[100:103]
	v_mfma_f32_16x16x32_bf16 v[84:87], v[172:175], v[210:213], v[84:87]
	v_mfma_f32_16x16x32_bf16 v[80:83], v[182:185], v[210:213], v[80:83]
	v_mfma_f32_16x16x32_bf16 v[64:67], v[182:185], v[218:221], v[64:67]
	v_mfma_f32_16x16x32_bf16 v[68:71], v[172:175], v[218:221], v[68:71]
	s_setprio 0
	s_barrier
	s_add_i32 s62, s46, s3
	v_lshl_add_u64 v[148:149], s[30:31], 0, v[132:133]
	s_mov_b32 m0, s62
	ds_read_b128 v[186:189], v155 offset:16384
	ds_read_b128 v[194:197], v155 offset:17408
	ds_read_b128 v[198:201], v155 offset:18432
	ds_read_b128 v[202:205], v155 offset:19456
	ds_read_b128 v[206:209], v155 offset:20480
	ds_read_b128 v[210:213], v155 offset:21504
	ds_read_b128 v[214:217], v155 offset:22528
	ds_read_b128 v[218:221], v155 offset:23552
	global_load_lds_dwordx4 v[148:149], off
	s_add_i32 m0, s62, 0x2000
	s_add_u32 s62, s30, 0x40000
	v_lshl_add_u64 v[190:191], s[30:31], 0, v[128:129]
	s_addc_u32 s63, s31, 0
	s_add_i32 s66, s47, s3
	global_load_lds_dwordx4 v[190:191], off
	v_lshl_add_u64 v[222:223], s[62:63], 0, v[132:133]
	s_mov_b32 m0, s66
	v_lshl_add_u64 v[224:225], s[36:37], 0, v[130:131]
	global_load_lds_dwordx4 v[222:223], off
	v_lshl_add_u64 v[222:223], s[62:63], 0, v[128:129]
	s_add_i32 m0, s66, 0x2000
	s_nop 0
	global_load_lds_dwordx4 v[222:223], off
	v_lshl_add_u64 v[222:223], s[36:37], 0, v[134:135]
	s_mov_b32 m0, s27
	s_nop 0
	global_load_lds_dwordx4 v[222:223], off
	s_mov_b32 m0, s33
	s_nop 0
	global_load_lds_dwordx4 v[224:225], off
	s_waitcnt vmcnt(8)
	s_waitcnt lgkmcnt(0)
	s_barrier
; #define PG8_STAGE(bufoff, gbase, voff) do { _Pragma("unroll") for (int _i = 0; _i < 2; ++_i) \
;         __builtin_amdgcn_global_load_lds((const unsigned*)((const char*)(gbase) + (voff)[_i]), (PG8_LAS unsigned*)(lds + (bufoff) + ldsw + _i * 8192), 16, 0, 0); } while (0)
; #define PG8_LDA(dst, b, h) do { _Pragma("unroll") for (int m = 0; m < 4; ++m) _Pragma("unroll") for (int k = 0; k < 2; ++k) dst[m][k] = *(const PG8_LAS bf16x8*)(lds + PG8_SA(b, h) + aoff + m * 2048 + k * 1024); } while (0)
; #define PG8_LDB(dst, b, h) do { _Pragma("unroll") for (int n = 0; n < 2; ++n) _Pragma("unroll") for (int k = 0; k < 2; ++k) dst[n][k] = *(const PG8_LAS bf16x8*)(lds + PG8_SB(b, h) + boff + n * 2048 + k * 1024); } while (0)
; #define PG8_MMA(ai, bj, At, Bt) do { __builtin_amdgcn_s_setprio(1); _Pragma("unroll") for (int m = 0; m < 4; ++m) _Pragma("unroll") for (int n = 0; n < 2; ++n) _Pragma("unroll") for (int k = 0; k < 2; ++k) \
;         acc[ai][bj][m][n] = __builtin_amdgcn_mfma_f32_16x16x32_bf16(Bt[n][k], At[m][k], acc[ai][bj][m][n], 0, 0, 0); __builtin_amdgcn_s_setprio(0); } while (0)
; #define PG8_WAIT_V(n) asm volatile("s_waitcnt vmcnt(" #n ")" ::: "memory")
; #define PG8_WAIT_L(n) asm volatile("s_waitcnt lgkmcnt(" #n ")" ::: "memory")
; #define PG8_BAR __builtin_amdgcn_s_barrier()
; #define PG8_SCHED __builtin_amdgcn_sched_barrier(0)
; template <class Epi, class Sched, bool ALIGN_EPI = false, bool SP2 = false>
; __device__ __forceinline__ void gemm_phase(PG8_LAS unsigned char* lds, const Gemm g, const Sched& S, const Epi& E) {
;     ...
;             PG8_WAIT_V(8); PG8_WAIT_L(0); PG8_BAR; PG8_MMA(1, 0, At, B0); PG8_MMA(1, 1, At, B1); PG8_BAR; PG8_SCHED;
;             PG8_LDB(B0, 1, 0); PG8_LDB(B1, 1, 1); PG8_SCHED; PG8_LDA(At, 1, 0); PG8_STAGE(PG8_SA(0, 1), a2 + hstep, voffA);
;             PG8_WAIT_V(8); PG8_WAIT_L(0); PG8_BAR; PG8_MMA(0, 0, At, B0); PG8_MMA(0, 1, At, B1); PG8_BAR; PG8_SCHED;
	s_setprio 1
	s_waitcnt lgkmcnt(0)
	v_mfma_f32_16x16x32_bf16 v[60:63], v[144:147], v[186:189], v[60:63]
	v_mfma_f32_16x16x32_bf16 v[56:59], v[160:163], v[186:189], v[56:59]
	v_mfma_f32_16x16x32_bf16 v[40:43], v[160:163], v[198:201], v[40:43]
	v_mfma_f32_16x16x32_bf16 v[44:47], v[144:147], v[198:201], v[44:47]
	v_mfma_f32_16x16x32_bf16 v[28:31], v[144:147], v[206:209], v[28:31]
	v_mfma_f32_16x16x32_bf16 v[24:27], v[160:163], v[206:209], v[24:27]
	v_mfma_f32_16x16x32_bf16 v[8:11], v[160:163], v[214:217], v[8:11]
	v_mfma_f32_16x16x32_bf16 v[12:15], v[144:147], v[214:217], v[12:15]
	v_mfma_f32_16x16x32_bf16 v[60:63], v[156:159], v[194:197], v[60:63]
	v_mfma_f32_16x16x32_bf16 v[56:59], v[164:167], v[194:197], v[56:59]
	v_mfma_f32_16x16x32_bf16 v[40:43], v[164:167], v[202:205], v[40:43]
	v_mfma_f32_16x16x32_bf16 v[44:47], v[156:159], v[202:205], v[44:47]
	v_mfma_f32_16x16x32_bf16 v[28:31], v[156:159], v[210:213], v[28:31]
	v_mfma_f32_16x16x32_bf16 v[24:27], v[164:167], v[210:213], v[24:27]
	v_mfma_f32_16x16x32_bf16 v[8:11], v[164:167], v[218:221], v[8:11]
	v_mfma_f32_16x16x32_bf16 v[12:15], v[156:159], v[218:221], v[12:15]
	s_setprio 0
	s_setprio 1
	v_mfma_f32_16x16x32_bf16 v[52:55], v[168:171], v[186:189], v[52:55]
	v_mfma_f32_16x16x32_bf16 v[48:51], v[176:179], v[186:189], v[48:51]
	v_mfma_f32_16x16x32_bf16 v[32:35], v[176:179], v[198:201], v[32:35]
	v_mfma_f32_16x16x32_bf16 v[36:39], v[168:171], v[198:201], v[36:39]
	v_mfma_f32_16x16x32_bf16 v[20:23], v[168:171], v[206:209], v[20:23]
	v_mfma_f32_16x16x32_bf16 v[16:19], v[176:179], v[206:209], v[16:19]
	v_mfma_f32_16x16x32_bf16 v[0:3], v[176:179], v[214:217], v[0:3]
	v_mfma_f32_16x16x32_bf16 v[4:7], v[168:171], v[214:217], v[4:7]
	v_mfma_f32_16x16x32_bf16 v[52:55], v[172:175], v[194:197], v[52:55]
	v_mfma_f32_16x16x32_bf16 v[48:51], v[182:185], v[194:197], v[48:51]
	v_mfma_f32_16x16x32_bf16 v[32:35], v[182:185], v[202:205], v[32:35]
	v_mfma_f32_16x16x32_bf16 v[36:39], v[172:175], v[202:205], v[36:39]
	v_mfma_f32_16x16x32_bf16 v[20:23], v[172:175], v[210:213], v[20:23]
	v_mfma_f32_16x16x32_bf16 v[16:19], v[182:185], v[210:213], v[16:19]
	v_mfma_f32_16x16x32_bf16 v[0:3], v[182:185], v[218:221], v[0:3]
	v_mfma_f32_16x16x32_bf16 v[4:7], v[172:175], v[218:221], v[4:7]
	s_setprio 0
	s_barrier
	s_add_i32 s62, 0, 0x18000
	s_add_i32 s63, 0, 0x1c000
	v_add_u32_e32 v164, s62, v151
	v_add_u32_e32 v181, s63, v151
	ds_read_b128 v[144:147], v164
	ds_read_b128 v[156:159], v164 offset:1024
	ds_read_b128 v[160:163], v164 offset:2048
	ds_read_b128 v[164:167], v164 offset:3072
	ds_read_b128 v[168:171], v181
	ds_read_b128 v[172:175], v181 offset:1024
	ds_read_b128 v[176:179], v181 offset:2048
	ds_read_b128 v[182:185], v181 offset:3072
	s_add_u32 s36, s36, 0x40000
	s_addc_u32 s37, s37, 0
	s_mov_b32 m0, s38
	v_lshl_add_u64 v[226:227], s[36:37], 0, v[134:135]
	ds_read_b128 v[186:189], v155 offset:32768
	ds_read_b128 v[194:197], v155 offset:33792
	ds_read_b128 v[198:201], v155 offset:34816
	ds_read_b128 v[202:205], v155 offset:35840
	ds_read_b128 v[206:209], v155 offset:36864
	ds_read_b128 v[210:213], v155 offset:37888
	ds_read_b128 v[214:217], v155 offset:38912
	ds_read_b128 v[218:221], v155 offset:39936
	global_load_lds_dwordx4 v[226:227], off
	v_lshl_add_u64 v[226:227], s[36:37], 0, v[130:131]
	s_mov_b32 m0, s39
	s_nop 0
	global_load_lds_dwordx4 v[226:227], off
	s_waitcnt vmcnt(8)
	s_waitcnt lgkmcnt(0)
	s_barrier
	s_setprio 1
	s_waitcnt lgkmcnt(0)
	v_mfma_f32_16x16x32_bf16 v[124:127], v[144:147], v[186:189], v[124:127]
	v_mfma_f32_16x16x32_bf16 v[120:123], v[160:163], v[186:189], v[120:123]
	v_mfma_f32_16x16x32_bf16 v[104:107], v[160:163], v[198:201], v[104:107]
	v_mfma_f32_16x16x32_bf16 v[108:111], v[144:147], v[198:201], v[108:111]
	v_mfma_f32_16x16x32_bf16 v[92:95], v[144:147], v[206:209], v[92:95]
	v_mfma_f32_16x16x32_bf16 v[88:91], v[160:163], v[206:209], v[88:91]
	v_mfma_f32_16x16x32_bf16 v[72:75], v[160:163], v[214:217], v[72:75]
	v_mfma_f32_16x16x32_bf16 v[76:79], v[144:147], v[214:217], v[76:79]
	v_mfma_f32_16x16x32_bf16 v[124:127], v[156:159], v[194:197], v[124:127]
	v_mfma_f32_16x16x32_bf16 v[120:123], v[164:167], v[194:197], v[120:123]
	v_mfma_f32_16x16x32_bf16 v[104:107], v[164:167], v[202:205], v[104:107]
	v_mfma_f32_16x16x32_bf16 v[108:111], v[156:159], v[202:205], v[108:111]
	v_mfma_f32_16x16x32_bf16 v[92:95], v[156:159], v[210:213], v[92:95]
	v_mfma_f32_16x16x32_bf16 v[88:91], v[164:167], v[210:213], v[88:91]
	v_mfma_f32_16x16x32_bf16 v[72:75], v[164:167], v[218:221], v[72:75]
	v_mfma_f32_16x16x32_bf16 v[76:79], v[156:159], v[218:221], v[76:79]
	s_setprio 0
	s_setprio 1
	v_mfma_f32_16x16x32_bf16 v[116:119], v[168:171], v[186:189], v[116:119]
	v_mfma_f32_16x16x32_bf16 v[112:115], v[176:179], v[186:189], v[112:115]
	v_mfma_f32_16x16x32_bf16 v[96:99], v[176:179], v[198:201], v[96:99]
	v_mfma_f32_16x16x32_bf16 v[100:103], v[168:171], v[198:201], v[100:103]
	v_mfma_f32_16x16x32_bf16 v[84:87], v[168:171], v[206:209], v[84:87]
	v_mfma_f32_16x16x32_bf16 v[80:83], v[176:179], v[206:209], v[80:83]
	v_mfma_f32_16x16x32_bf16 v[64:67], v[176:179], v[214:217], v[64:67]
	v_mfma_f32_16x16x32_bf16 v[68:71], v[168:171], v[214:217], v[68:71]
	v_mfma_f32_16x16x32_bf16 v[116:119], v[172:175], v[194:197], v[116:119]
	v_mfma_f32_16x16x32_bf16 v[112:115], v[182:185], v[194:197], v[112:115]
	v_mfma_f32_16x16x32_bf16 v[96:99], v[182:185], v[202:205], v[96:99]
	v_mfma_f32_16x16x32_bf16 v[100:103], v[172:175], v[202:205], v[100:103]
	v_mfma_f32_16x16x32_bf16 v[84:87], v[172:175], v[210:213], v[84:87]
	v_mfma_f32_16x16x32_bf16 v[80:83], v[182:185], v[210:213], v[80:83]
	v_mfma_f32_16x16x32_bf16 v[64:67], v[182:185], v[218:221], v[64:67]
	v_mfma_f32_16x16x32_bf16 v[68:71], v[172:175], v[218:221], v[68:71]
	s_setprio 0
	s_barrier
; #define PG8_STAGE(bufoff, gbase, voff) do { _Pragma("unroll") for (int _i = 0; _i < 2; ++_i) \
;         __builtin_amdgcn_global_load_lds((const unsigned*)((const char*)(gbase) + (voff)[_i]), (PG8_LAS unsigned*)(lds + (bufoff) + ldsw + _i * 8192), 16, 0, 0); } while (0)
; #define PG8_LDA(dst, b, h) do { _Pragma("unroll") for (int m = 0; m < 4; ++m) _Pragma("unroll") for (int k = 0; k < 2; ++k) dst[m][k] = *(const PG8_LAS bf16x8*)(lds + PG8_SA(b, h) + aoff + m * 2048 + k * 1024); } while (0)
; #define PG8_MMA(ai, bj, At, Bt) do { __builtin_amdgcn_s_setprio(1); _Pragma("unroll") for (int m = 0; m < 4; ++m) _Pragma("unroll") for (int n = 0; n < 2; ++n) _Pragma("unroll") for (int k = 0; k < 2; ++k) \
;         acc[ai][bj][m][n] = __builtin_amdgcn_mfma_f32_16x16x32_bf16(Bt[n][k], At[m][k], acc[ai][bj][m][n], 0, 0, 0); __builtin_amdgcn_s_setprio(0); } while (0)
; #define PG8_WAIT_V(n) asm volatile("s_waitcnt vmcnt(" #n ")" ::: "memory")
; #define PG8_WAIT_L(n) asm volatile("s_waitcnt lgkmcnt(" #n ")" ::: "memory")
; #define PG8_BAR __builtin_amdgcn_s_barrier()
; #define PG8_SCHED __builtin_amdgcn_sched_barrier(0)
; template <class Epi, class Sched, bool ALIGN_EPI = false, bool SP2 = false>
; __device__ __forceinline__ void gemm_phase(PG8_LAS unsigned char* lds, const Gemm g, const Sched& S, const Epi& E) {
;     ...
;         for (int t = 0; t < nt; t += 2) {
;     ...
;             PG8_LDA(At, 1, 1); PG8_STAGE(PG8_SB(1, 0), b3, voffB); PG8_STAGE(PG8_SB(1, 1), b3 + hstep, voffB); PG8_STAGE(PG8_SA(1, 0), a3, voffA);
;             PG8_WAIT_V(8); PG8_WAIT_L(0); PG8_BAR; PG8_MMA(1, 0, At, B0); PG8_MMA(1, 1, At, B1); PG8_BAR; PG8_SCHED;
;     ...
;         if constexpr (ALIGN_EPI) { if (wr == 0) PG8_BAR; }
	s_add_i32 s36, s62, s3
	v_lshl_add_u64 v[148:149], v[148:149], 0, s[6:7]
	s_mov_b32 m0, s36
	ds_read_b128 v[186:189], v155 offset:49152
	ds_read_b128 v[194:197], v155 offset:50176
	ds_read_b128 v[198:201], v155 offset:51200
	ds_read_b128 v[202:205], v155 offset:52224
	ds_read_b128 v[206:209], v155 offset:53248
	ds_read_b128 v[210:213], v155 offset:54272
	ds_read_b128 v[214:217], v155 offset:55296
	ds_read_b128 v[218:221], v155 offset:56320
	global_load_lds_dwordx4 v[148:149], off
	s_add_i32 m0, s36, 0x2000
	s_add_u32 s30, s30, 0x40080
	v_lshl_add_u64 v[148:149], v[190:191], 0, s[6:7]
	s_addc_u32 s31, s31, 0
	s_add_i32 s36, s63, s3
	global_load_lds_dwordx4 v[148:149], off
	v_lshl_add_u64 v[148:149], s[30:31], 0, v[132:133]
	s_mov_b32 m0, s36
	s_nop 0
	global_load_lds_dwordx4 v[148:149], off
	v_lshl_add_u64 v[148:149], s[30:31], 0, v[128:129]
	s_add_i32 m0, s36, 0x2000
	s_nop 0
	global_load_lds_dwordx4 v[148:149], off
	v_lshl_add_u64 v[148:149], v[222:223], 0, s[6:7]
	s_mov_b32 m0, s42
	s_nop 0
	global_load_lds_dwordx4 v[148:149], off
	v_lshl_add_u64 v[148:149], v[224:225], 0, s[6:7]
	s_mov_b32 m0, s43
	s_nop 0
	global_load_lds_dwordx4 v[148:149], off
	s_waitcnt vmcnt(8)
	s_waitcnt lgkmcnt(0)
	s_barrier
	s_setprio 1
	s_waitcnt lgkmcnt(0)
	v_mfma_f32_16x16x32_bf16 v[60:63], v[144:147], v[186:189], v[60:63]
	v_mfma_f32_16x16x32_bf16 v[56:59], v[160:163], v[186:189], v[56:59]
	v_mfma_f32_16x16x32_bf16 v[40:43], v[160:163], v[198:201], v[40:43]
	v_mfma_f32_16x16x32_bf16 v[44:47], v[144:147], v[198:201], v[44:47]
	v_mfma_f32_16x16x32_bf16 v[28:31], v[144:147], v[206:209], v[28:31]
	v_mfma_f32_16x16x32_bf16 v[24:27], v[160:163], v[206:209], v[24:27]
	v_mfma_f32_16x16x32_bf16 v[8:11], v[160:163], v[214:217], v[8:11]
	v_mfma_f32_16x16x32_bf16 v[12:15], v[144:147], v[214:217], v[12:15]
	v_mfma_f32_16x16x32_bf16 v[60:63], v[156:159], v[194:197], v[60:63]
	v_mfma_f32_16x16x32_bf16 v[56:59], v[164:167], v[194:197], v[56:59]
	v_mfma_f32_16x16x32_bf16 v[40:43], v[164:167], v[202:205], v[40:43]
	v_mfma_f32_16x16x32_bf16 v[44:47], v[156:159], v[202:205], v[44:47]
	v_mfma_f32_16x16x32_bf16 v[28:31], v[156:159], v[210:213], v[28:31]
	v_mfma_f32_16x16x32_bf16 v[24:27], v[164:167], v[210:213], v[24:27]
	v_mfma_f32_16x16x32_bf16 v[8:11], v[164:167], v[218:221], v[8:11]
	v_mfma_f32_16x16x32_bf16 v[12:15], v[156:159], v[218:221], v[12:15]
	s_setprio 0
	s_setprio 1
	v_mfma_f32_16x16x32_bf16 v[52:55], v[168:171], v[186:189], v[52:55]
	v_mfma_f32_16x16x32_bf16 v[48:51], v[176:179], v[186:189], v[48:51]
	v_mfma_f32_16x16x32_bf16 v[32:35], v[176:179], v[198:201], v[32:35]
	v_mfma_f32_16x16x32_bf16 v[36:39], v[168:171], v[198:201], v[36:39]
	v_mfma_f32_16x16x32_bf16 v[20:23], v[168:171], v[206:209], v[20:23]
	v_mfma_f32_16x16x32_bf16 v[16:19], v[176:179], v[206:209], v[16:19]
	v_mfma_f32_16x16x32_bf16 v[0:3], v[176:179], v[214:217], v[0:3]
	v_mfma_f32_16x16x32_bf16 v[4:7], v[168:171], v[214:217], v[4:7]
	v_mfma_f32_16x16x32_bf16 v[52:55], v[172:175], v[194:197], v[52:55]
	v_mfma_f32_16x16x32_bf16 v[48:51], v[182:185], v[194:197], v[48:51]
	v_mfma_f32_16x16x32_bf16 v[32:35], v[182:185], v[202:205], v[32:35]
	v_mfma_f32_16x16x32_bf16 v[36:39], v[172:175], v[202:205], v[36:39]
	v_mfma_f32_16x16x32_bf16 v[20:23], v[172:175], v[210:213], v[20:23]
	v_mfma_f32_16x16x32_bf16 v[16:19], v[182:185], v[210:213], v[16:19]
	v_mfma_f32_16x16x32_bf16 v[0:3], v[182:185], v[218:221], v[0:3]
	v_mfma_f32_16x16x32_bf16 v[4:7], v[172:175], v[218:221], v[4:7]
	s_setprio 0
	s_barrier
	s_add_i32 s53, s53, 2
	s_add_u32 s28, s28, 0x100
	s_addc_u32 s29, s29, 0
	s_add_u32 s51, s51, 0x100
	s_addc_u32 s52, s52, 0
	s_cmp_gt_u32 s53, 13
	s_cbranch_scc0 .LBB0_513
	s_and_b64 vcc, exec, s[8:9]
	s_cbranch_vccz .LBB0_516
	s_barrier

; #define PG8_STAGE(bufoff, gbase, voff) do { _Pragma("unroll") for (int _i = 0; _i < 2; ++_i) \
;         __builtin_amdgcn_global_load_lds((const unsigned*)((const char*)(gbase) + (voff)[_i]), (PG8_LAS unsigned*)(lds + (bufoff) + ldsw + _i * 8192), 16, 0, 0); } while (0)
; #define PG8_LDA(dst, b, h) do { _Pragma("unroll") for (int m = 0; m < 4; ++m) _Pragma("unroll") for (int k = 0; k < 2; ++k) dst[m][k] = *(const PG8_LAS bf16x8*)(lds + PG8_SA(b, h) + aoff + m * 2048 + k * 1024); } while (0)
; #define PG8_LDB(dst, b, h) do { _Pragma("unroll") for (int n = 0; n < 2; ++n) _Pragma("unroll") for (int k = 0; k < 2; ++k) dst[n][k] = *(const PG8_LAS bf16x8*)(lds + PG8_SB(b, h) + boff + n * 2048 + k * 1024); } while (0)
; #define PG8_MMA(ai, bj, At, Bt) do { __builtin_amdgcn_s_setprio(1); _Pragma("unroll") for (int m = 0; m < 4; ++m) _Pragma("unroll") for (int n = 0; n < 2; ++n) _Pragma("unroll") for (int k = 0; k < 2; ++k) \
;         acc[ai][bj][m][n] = __builtin_amdgcn_mfma_f32_16x16x32_bf16(Bt[n][k], At[m][k], acc[ai][bj][m][n], 0, 0, 0); __builtin_amdgcn_s_setprio(0); } while (0)
; #define PG8_WAIT_V(n) asm volatile("s_waitcnt vmcnt(" #n ")" ::: "memory")
; #define PG8_BAR __builtin_amdgcn_s_barrier()
; template <class Epi, class Sched, bool ALIGN_EPI = false, bool SP2 = false>
; __device__ __forceinline__ void gemm_phase(PG8_LAS unsigned char* lds, const Gemm g, const Sched& S, const Epi& E) {
;     ...
;         for (int t = 0; t < nt; t += 2) {
;             const bool last = (t == nt - 2);
;             const char* a1 = cA + (size_t)(t + 1) * kstep;
;             const char* a2 = last ? nA : cA + (size_t)(t + 2) * kstep; const char* b2 = last ? nB : cB + (size_t)(t + 2) * kstep;
;             const char* a3 = a2 + kstep; const char* b3 = b2 + kstep;
;             if (last && has_next) S.a_ready(nxt);
;             if constexpr (SP2) {
;             PG8_LDB(B0, 0, 0); PG8_LDB(B1, 0, 1); PG8_SCHED; PG8_LDA(At, 0, 0); PG8_STAGE(PG8_SA(1, 1), a1 + hstep, voffA);
;             PG8_WAIT_V(8); PG8_WAIT_L(0); PG8_BAR; PG8_MMA(0, 0, At, B0); PG8_MMA(0, 1, At, B1); PG8_BAR; PG8_SCHED;
;             PG8_LDA(At, 0, 1); PG8_STAGE(PG8_SB(0, 0), b2, voffB); PG8_STAGE(PG8_SB(0, 1), b2 + hstep, voffB); PG8_STAGE(PG8_SA(0, 0), a2, voffA);
;             PG8_WAIT_V(8); PG8_WAIT_L(0); PG8_BAR; PG8_MMA(1, 0, At, B0); PG8_MMA(1, 1, At, B1); PG8_BAR; PG8_SCHED;
.LBB0_586:
	s_add_u32 s22, s48, s18
	s_addc_u32 s23, s49, s19
	s_add_u32 s22, s22, 0xb000100
	s_addc_u32 s23, s23, 0
	s_add_u32 s53, s50, s18
	s_addc_u32 s62, s51, s19
	s_add_i32 s63, 0, 0x10000
	s_cmpk_eq_i32 s18, 0x700
	s_cselect_b32 s25, s5, s23
	s_cselect_b32 s24, s4, s22
	v_add_u32_e32 v161, s63, v159
	s_cselect_b32 s23, s1, s62
	s_cselect_b32 s22, s0, s53
	s_add_i32 s53, 0, 0x14000
	ds_read_b128 v[162:165], v161
	ds_read_b128 v[166:169], v161 offset:1024
	ds_read_b128 v[170:173], v161 offset:2048
	ds_read_b128 v[174:177], v161 offset:3072
	v_add_u32_e32 v161, s53, v159
	ds_read_b128 v[182:185], v161
	ds_read_b128 v[186:189], v161 offset:1024
	ds_read_b128 v[194:197], v161 offset:2048
	ds_read_b128 v[198:201], v161 offset:3072
	v_lshl_add_u64 v[178:179], v[140:141], 0, s[18:19]
	s_add_i32 m0, s16, 0xc000
	ds_read_b128 v[202:205], v160
	ds_read_b128 v[206:209], v160 offset:1024
	ds_read_b128 v[210:213], v160 offset:2048
	ds_read_b128 v[214:217], v160 offset:3072
	ds_read_b128 v[218:221], v160 offset:4096
	ds_read_b128 v[222:225], v160 offset:5120
	ds_read_b128 v[226:229], v160 offset:6144
	ds_read_b128 v[230:233], v160 offset:7168
	global_load_lds_dwordx4 v[178:179], off
	v_lshl_add_u64 v[178:179], v[142:143], 0, s[18:19]
	s_add_i32 m0, s16, 0xe000
	s_nop 0
	global_load_lds_dwordx4 v[178:179], off
	s_waitcnt vmcnt(8)
	s_waitcnt lgkmcnt(0)
	s_barrier
	s_setprio 1
	s_waitcnt lgkmcnt(0)
	v_mfma_f32_16x16x32_bf16 v[124:127], v[162:165], v[202:205], v[124:127]
	v_mfma_f32_16x16x32_bf16 v[120:123], v[170:173], v[202:205], v[120:123]
	v_mfma_f32_16x16x32_bf16 v[108:111], v[170:173], v[210:213], v[108:111]
	v_mfma_f32_16x16x32_bf16 v[112:115], v[162:165], v[210:213], v[112:115]
	v_mfma_f32_16x16x32_bf16 v[100:103], v[162:165], v[218:221], v[100:103]
	v_mfma_f32_16x16x32_bf16 v[92:95], v[170:173], v[218:221], v[92:95]
	v_mfma_f32_16x16x32_bf16 v[76:79], v[170:173], v[226:229], v[76:79]
	v_mfma_f32_16x16x32_bf16 v[84:87], v[162:165], v[226:229], v[84:87]
	v_mfma_f32_16x16x32_bf16 v[124:127], v[166:169], v[206:209], v[124:127]
	v_mfma_f32_16x16x32_bf16 v[120:123], v[174:177], v[206:209], v[120:123]
	v_mfma_f32_16x16x32_bf16 v[108:111], v[174:177], v[214:217], v[108:111]
	v_mfma_f32_16x16x32_bf16 v[112:115], v[166:169], v[214:217], v[112:115]
	v_mfma_f32_16x16x32_bf16 v[100:103], v[166:169], v[222:225], v[100:103]
	v_mfma_f32_16x16x32_bf16 v[92:95], v[174:177], v[222:225], v[92:95]
	v_mfma_f32_16x16x32_bf16 v[76:79], v[174:177], v[230:233], v[76:79]
	v_mfma_f32_16x16x32_bf16 v[84:87], v[166:169], v[230:233], v[84:87]
	s_setprio 0
	s_setprio 1
	v_mfma_f32_16x16x32_bf16 v[116:119], v[182:185], v[202:205], v[116:119]
	v_mfma_f32_16x16x32_bf16 v[104:107], v[194:197], v[202:205], v[104:107]
	v_mfma_f32_16x16x32_bf16 v[88:91], v[194:197], v[210:213], v[88:91]
	v_mfma_f32_16x16x32_bf16 v[96:99], v[182:185], v[210:213], v[96:99]
	v_mfma_f32_16x16x32_bf16 v[80:83], v[182:185], v[218:221], v[80:83]
	v_mfma_f32_16x16x32_bf16 v[72:75], v[194:197], v[218:221], v[72:75]
	v_mfma_f32_16x16x32_bf16 v[64:67], v[194:197], v[226:229], v[64:67]
	v_mfma_f32_16x16x32_bf16 v[68:71], v[182:185], v[226:229], v[68:71]
	v_mfma_f32_16x16x32_bf16 v[116:119], v[186:189], v[206:209], v[116:119]
	v_mfma_f32_16x16x32_bf16 v[104:107], v[198:201], v[206:209], v[104:107]
	v_mfma_f32_16x16x32_bf16 v[88:91], v[198:201], v[214:217], v[88:91]
	v_mfma_f32_16x16x32_bf16 v[96:99], v[186:189], v[214:217], v[96:99]
	v_mfma_f32_16x16x32_bf16 v[80:83], v[186:189], v[222:225], v[80:83]
	v_mfma_f32_16x16x32_bf16 v[72:75], v[198:201], v[222:225], v[72:75]
	v_mfma_f32_16x16x32_bf16 v[64:67], v[198:201], v[230:233], v[64:67]
	v_mfma_f32_16x16x32_bf16 v[68:71], v[186:189], v[230:233], v[68:71]
	s_setprio 0
	s_barrier
	s_add_i32 s62, s63, s13
	v_lshl_add_u64 v[178:179], s[22:23], 0, v[128:129]
	s_mov_b32 m0, s62
	ds_read_b128 v[202:205], v160 offset:16384
	ds_read_b128 v[206:209], v160 offset:17408
	ds_read_b128 v[210:213], v160 offset:18432
	ds_read_b128 v[214:217], v160 offset:19456
	ds_read_b128 v[218:221], v160 offset:20480
	ds_read_b128 v[222:225], v160 offset:21504
	ds_read_b128 v[226:229], v160 offset:22528
	ds_read_b128 v[230:233], v160 offset:23552
	global_load_lds_dwordx4 v[178:179], off
	s_add_i32 m0, s62, 0x2000
	s_add_u32 s62, s22, 0x40000
	v_lshl_add_u64 v[190:191], s[22:23], 0, v[130:131]
	s_addc_u32 s63, s23, 0
	s_add_i32 s53, s53, s13
	global_load_lds_dwordx4 v[190:191], off
	v_lshl_add_u64 v[234:235], s[62:63], 0, v[128:129]
	s_mov_b32 m0, s53
	v_lshl_add_u64 v[236:237], s[24:25], 0, v[130:131]
	global_load_lds_dwordx4 v[234:235], off
	v_lshl_add_u64 v[234:235], s[62:63], 0, v[130:131]
	s_add_i32 m0, s53, 0x2000
	s_nop 0
	global_load_lds_dwordx4 v[234:235], off
	v_lshl_add_u64 v[234:235], s[24:25], 0, v[128:129]
	s_mov_b32 m0, s16
	s_nop 0
	global_load_lds_dwordx4 v[234:235], off
	s_mov_b32 m0, s43
	s_nop 0
	global_load_lds_dwordx4 v[236:237], off
	s_waitcnt vmcnt(8)
	s_waitcnt lgkmcnt(0)
	s_barrier
; #define PG8_STAGE(bufoff, gbase, voff) do { _Pragma("unroll") for (int _i = 0; _i < 2; ++_i) \
;         __builtin_amdgcn_global_load_lds((const unsigned*)((const char*)(gbase) + (voff)[_i]), (PG8_LAS unsigned*)(lds + (bufoff) + ldsw + _i * 8192), 16, 0, 0); } while (0)
; #define PG8_LDA(dst, b, h) do { _Pragma("unroll") for (int m = 0; m < 4; ++m) _Pragma("unroll") for (int k = 0; k < 2; ++k) dst[m][k] = *(const PG8_LAS bf16x8*)(lds + PG8_SA(b, h) + aoff + m * 2048 + k * 1024); } while (0)
; #define PG8_LDB(dst, b, h) do { _Pragma("unroll") for (int n = 0; n < 2; ++n) _Pragma("unroll") for (int k = 0; k < 2; ++k) dst[n][k] = *(const PG8_LAS bf16x8*)(lds + PG8_SB(b, h) + boff + n * 2048 + k * 1024); } while (0)
; #define PG8_MMA(ai, bj, At, Bt) do { __builtin_amdgcn_s_setprio(1); _Pragma("unroll") for (int m = 0; m < 4; ++m) _Pragma("unroll") for (int n = 0; n < 2; ++n) _Pragma("unroll") for (int k = 0; k < 2; ++k) \
;         acc[ai][bj][m][n] = __builtin_amdgcn_mfma_f32_16x16x32_bf16(Bt[n][k], At[m][k], acc[ai][bj][m][n], 0, 0, 0); __builtin_amdgcn_s_setprio(0); } while (0)
; #define PG8_WAIT_V(n) asm volatile("s_waitcnt vmcnt(" #n ")" ::: "memory")
; #define PG8_WAIT_L(n) asm volatile("s_waitcnt lgkmcnt(" #n ")" ::: "memory")
; #define PG8_BAR __builtin_amdgcn_s_barrier()
; #define PG8_SCHED __builtin_amdgcn_sched_barrier(0)
; template <class Epi, class Sched, bool ALIGN_EPI = false, bool SP2 = false>
; __device__ __forceinline__ void gemm_phase(PG8_LAS unsigned char* lds, const Gemm g, const Sched& S, const Epi& E) {
;     ...
;             PG8_WAIT_V(8); PG8_WAIT_L(0); PG8_BAR; PG8_MMA(1, 0, At, B0); PG8_MMA(1, 1, At, B1); PG8_BAR; PG8_SCHED;
;             PG8_LDB(B0, 1, 0); PG8_LDB(B1, 1, 1); PG8_SCHED; PG8_LDA(At, 1, 0); PG8_STAGE(PG8_SA(0, 1), a2 + hstep, voffA);
;             PG8_WAIT_V(8); PG8_WAIT_L(0); PG8_BAR; PG8_MMA(0, 0, At, B0); PG8_MMA(0, 1, At, B1); PG8_BAR; PG8_SCHED;
	s_setprio 1
	s_waitcnt lgkmcnt(0)
	v_mfma_f32_16x16x32_bf16 v[60:63], v[162:165], v[202:205], v[60:63]
	v_mfma_f32_16x16x32_bf16 v[56:59], v[170:173], v[202:205], v[56:59]
	v_mfma_f32_16x16x32_bf16 v[44:47], v[170:173], v[210:213], v[44:47]
	v_mfma_f32_16x16x32_bf16 v[52:55], v[162:165], v[210:213], v[52:55]
	v_mfma_f32_16x16x32_bf16 v[36:39], v[162:165], v[218:221], v[36:39]
	v_mfma_f32_16x16x32_bf16 v[32:35], v[170:173], v[218:221], v[32:35]
	v_mfma_f32_16x16x32_bf16 v[16:19], v[170:173], v[226:229], v[16:19]
	v_mfma_f32_16x16x32_bf16 v[20:23], v[162:165], v[226:229], v[20:23]
	v_mfma_f32_16x16x32_bf16 v[60:63], v[166:169], v[206:209], v[60:63]
	v_mfma_f32_16x16x32_bf16 v[56:59], v[174:177], v[206:209], v[56:59]
	v_mfma_f32_16x16x32_bf16 v[44:47], v[174:177], v[214:217], v[44:47]
	v_mfma_f32_16x16x32_bf16 v[52:55], v[166:169], v[214:217], v[52:55]
	v_mfma_f32_16x16x32_bf16 v[36:39], v[166:169], v[222:225], v[36:39]
	v_mfma_f32_16x16x32_bf16 v[32:35], v[174:177], v[222:225], v[32:35]
	v_mfma_f32_16x16x32_bf16 v[16:19], v[174:177], v[230:233], v[16:19]
	v_mfma_f32_16x16x32_bf16 v[20:23], v[166:169], v[230:233], v[20:23]
	s_setprio 0
	s_setprio 1
	v_mfma_f32_16x16x32_bf16 v[48:51], v[182:185], v[202:205], v[48:51]
	v_mfma_f32_16x16x32_bf16 v[40:43], v[194:197], v[202:205], v[40:43]
	v_mfma_f32_16x16x32_bf16 v[24:27], v[194:197], v[210:213], v[24:27]
	v_mfma_f32_16x16x32_bf16 v[28:31], v[182:185], v[210:213], v[28:31]
	v_mfma_f32_16x16x32_bf16 v[12:15], v[182:185], v[218:221], v[12:15]
	v_mfma_f32_16x16x32_bf16 v[8:11], v[194:197], v[218:221], v[8:11]
	v_mfma_f32_16x16x32_bf16 v[0:3], v[194:197], v[226:229], v[0:3]
	v_mfma_f32_16x16x32_bf16 v[4:7], v[182:185], v[226:229], v[4:7]
	v_mfma_f32_16x16x32_bf16 v[48:51], v[186:189], v[206:209], v[48:51]
	v_mfma_f32_16x16x32_bf16 v[40:43], v[198:201], v[206:209], v[40:43]
	v_mfma_f32_16x16x32_bf16 v[24:27], v[198:201], v[214:217], v[24:27]
	v_mfma_f32_16x16x32_bf16 v[28:31], v[186:189], v[214:217], v[28:31]
	v_mfma_f32_16x16x32_bf16 v[12:15], v[186:189], v[222:225], v[12:15]
	v_mfma_f32_16x16x32_bf16 v[8:11], v[198:201], v[222:225], v[8:11]
	v_mfma_f32_16x16x32_bf16 v[0:3], v[198:201], v[230:233], v[0:3]
	v_mfma_f32_16x16x32_bf16 v[4:7], v[186:189], v[230:233], v[4:7]
	s_setprio 0
	s_barrier
	s_add_i32 s53, 0, 0x18000
	v_add_u32_e32 v161, s53, v159
	s_add_i32 s62, 0, 0x1c000
	ds_read_b128 v[162:165], v161
	ds_read_b128 v[166:169], v161 offset:1024
	ds_read_b128 v[170:173], v161 offset:2048
	ds_read_b128 v[174:177], v161 offset:3072
	v_add_u32_e32 v161, s62, v159
	ds_read_b128 v[182:185], v161
	ds_read_b128 v[186:189], v161 offset:1024
	ds_read_b128 v[194:197], v161 offset:2048
	ds_read_b128 v[198:201], v161 offset:3072
	s_add_u32 s24, s24, 0x40000
	s_addc_u32 s25, s25, 0
	s_mov_b32 m0, s44
	v_lshl_add_u64 v[238:239], s[24:25], 0, v[128:129]
	ds_read_b128 v[202:205], v160 offset:32768
	ds_read_b128 v[206:209], v160 offset:33792
	ds_read_b128 v[210:213], v160 offset:34816
	ds_read_b128 v[214:217], v160 offset:35840
	ds_read_b128 v[218:221], v160 offset:36864
	ds_read_b128 v[222:225], v160 offset:37888
	ds_read_b128 v[226:229], v160 offset:38912
	ds_read_b128 v[230:233], v160 offset:39936
	global_load_lds_dwordx4 v[238:239], off
	v_lshl_add_u64 v[238:239], s[24:25], 0, v[130:131]
	s_mov_b32 m0, s45
	s_nop 0
	global_load_lds_dwordx4 v[238:239], off
	s_waitcnt vmcnt(8)
	s_waitcnt lgkmcnt(0)
	s_barrier
	s_setprio 1
	s_waitcnt lgkmcnt(0)
	v_mfma_f32_16x16x32_bf16 v[124:127], v[162:165], v[202:205], v[124:127]
	v_mfma_f32_16x16x32_bf16 v[120:123], v[170:173], v[202:205], v[120:123]
	v_mfma_f32_16x16x32_bf16 v[108:111], v[170:173], v[210:213], v[108:111]
	v_mfma_f32_16x16x32_bf16 v[112:115], v[162:165], v[210:213], v[112:115]
	v_mfma_f32_16x16x32_bf16 v[100:103], v[162:165], v[218:221], v[100:103]
	v_mfma_f32_16x16x32_bf16 v[92:95], v[170:173], v[218:221], v[92:95]
	v_mfma_f32_16x16x32_bf16 v[76:79], v[170:173], v[226:229], v[76:79]
	v_mfma_f32_16x16x32_bf16 v[84:87], v[162:165], v[226:229], v[84:87]
	v_mfma_f32_16x16x32_bf16 v[124:127], v[166:169], v[206:209], v[124:127]
	v_mfma_f32_16x16x32_bf16 v[120:123], v[174:177], v[206:209], v[120:123]
	v_mfma_f32_16x16x32_bf16 v[108:111], v[174:177], v[214:217], v[108:111]
	v_mfma_f32_16x16x32_bf16 v[112:115], v[166:169], v[214:217], v[112:115]
	v_mfma_f32_16x16x32_bf16 v[100:103], v[166:169], v[222:225], v[100:103]
	v_mfma_f32_16x16x32_bf16 v[92:95], v[174:177], v[222:225], v[92:95]
	v_mfma_f32_16x16x32_bf16 v[76:79], v[174:177], v[230:233], v[76:79]
	v_mfma_f32_16x16x32_bf16 v[84:87], v[166:169], v[230:233], v[84:87]
	s_setprio 0
	s_setprio 1
	v_mfma_f32_16x16x32_bf16 v[116:119], v[182:185], v[202:205], v[116:119]
	v_mfma_f32_16x16x32_bf16 v[104:107], v[194:197], v[202:205], v[104:107]
	v_mfma_f32_16x16x32_bf16 v[88:91], v[194:197], v[210:213], v[88:91]
	v_mfma_f32_16x16x32_bf16 v[96:99], v[182:185], v[210:213], v[96:99]
	v_mfma_f32_16x16x32_bf16 v[80:83], v[182:185], v[218:221], v[80:83]
	v_mfma_f32_16x16x32_bf16 v[72:75], v[194:197], v[218:221], v[72:75]
	v_mfma_f32_16x16x32_bf16 v[64:67], v[194:197], v[226:229], v[64:67]
	v_mfma_f32_16x16x32_bf16 v[68:71], v[182:185], v[226:229], v[68:71]
	v_mfma_f32_16x16x32_bf16 v[116:119], v[186:189], v[206:209], v[116:119]
	v_mfma_f32_16x16x32_bf16 v[104:107], v[198:201], v[206:209], v[104:107]
	v_mfma_f32_16x16x32_bf16 v[88:91], v[198:201], v[214:217], v[88:91]
	v_mfma_f32_16x16x32_bf16 v[96:99], v[186:189], v[214:217], v[96:99]
	v_mfma_f32_16x16x32_bf16 v[80:83], v[186:189], v[222:225], v[80:83]
	v_mfma_f32_16x16x32_bf16 v[72:75], v[198:201], v[222:225], v[72:75]
	v_mfma_f32_16x16x32_bf16 v[64:67], v[198:201], v[230:233], v[64:67]
	v_mfma_f32_16x16x32_bf16 v[68:71], v[186:189], v[230:233], v[68:71]
	s_setprio 0
	s_barrier
; #define PG8_STAGE(bufoff, gbase, voff) do { _Pragma("unroll") for (int _i = 0; _i < 2; ++_i) \
;         __builtin_amdgcn_global_load_lds((const unsigned*)((const char*)(gbase) + (voff)[_i]), (PG8_LAS unsigned*)(lds + (bufoff) + ldsw + _i * 8192), 16, 0, 0); } while (0)
; #define PG8_LDA(dst, b, h) do { _Pragma("unroll") for (int m = 0; m < 4; ++m) _Pragma("unroll") for (int k = 0; k < 2; ++k) dst[m][k] = *(const PG8_LAS bf16x8*)(lds + PG8_SA(b, h) + aoff + m * 2048 + k * 1024); } while (0)
; #define PG8_MMA(ai, bj, At, Bt) do { __builtin_amdgcn_s_setprio(1); _Pragma("unroll") for (int m = 0; m < 4; ++m) _Pragma("unroll") for (int n = 0; n < 2; ++n) _Pragma("unroll") for (int k = 0; k < 2; ++k) \
;         acc[ai][bj][m][n] = __builtin_amdgcn_mfma_f32_16x16x32_bf16(Bt[n][k], At[m][k], acc[ai][bj][m][n], 0, 0, 0); __builtin_amdgcn_s_setprio(0); } while (0)
; #define PG8_WAIT_V(n) asm volatile("s_waitcnt vmcnt(" #n ")" ::: "memory")
; #define PG8_WAIT_L(n) asm volatile("s_waitcnt lgkmcnt(" #n ")" ::: "memory")
; #define PG8_BAR __builtin_amdgcn_s_barrier()
; #define PG8_SCHED __builtin_amdgcn_sched_barrier(0)
; template <class Epi, class Sched, bool ALIGN_EPI = false, bool SP2 = false>
; __device__ __forceinline__ void gemm_phase(PG8_LAS unsigned char* lds, const Gemm g, const Sched& S, const Epi& E) {
;     ...
;         for (int t = 0; t < nt; t += 2) {
;     ...
;             PG8_LDA(At, 1, 1); PG8_STAGE(PG8_SB(1, 0), b3, voffB); PG8_STAGE(PG8_SB(1, 1), b3 + hstep, voffB); PG8_STAGE(PG8_SA(1, 0), a3, voffA);
;             PG8_WAIT_V(8); PG8_WAIT_L(0); PG8_BAR; PG8_MMA(1, 0, At, B0); PG8_MMA(1, 1, At, B1); PG8_BAR; PG8_SCHED;
;     ...
;     PG8_WAIT_V(0);
;     if constexpr (!ALIGN_EPI) { if (wr == 0) PG8_BAR; }
	s_add_i32 s24, s53, s13
	v_lshl_add_u64 v[178:179], v[178:179], 0, s[14:15]
	s_mov_b32 m0, s24
	ds_read_b128 v[202:205], v160 offset:49152
	ds_read_b128 v[206:209], v160 offset:50176
	ds_read_b128 v[210:213], v160 offset:51200
	ds_read_b128 v[214:217], v160 offset:52224
	ds_read_b128 v[218:221], v160 offset:53248
	ds_read_b128 v[222:225], v160 offset:54272
	ds_read_b128 v[226:229], v160 offset:55296
	ds_read_b128 v[230:233], v160 offset:56320
	global_load_lds_dwordx4 v[178:179], off
	s_add_i32 m0, s24, 0x2000
	s_add_u32 s22, s22, 0x40080
	v_lshl_add_u64 v[178:179], v[190:191], 0, s[14:15]
	s_addc_u32 s23, s23, 0
	s_add_i32 s24, s62, s13
	global_load_lds_dwordx4 v[178:179], off
	v_lshl_add_u64 v[178:179], s[22:23], 0, v[128:129]
	s_mov_b32 m0, s24
	s_nop 0
	global_load_lds_dwordx4 v[178:179], off
	v_lshl_add_u64 v[178:179], s[22:23], 0, v[130:131]
	s_add_i32 m0, s24, 0x2000
	s_nop 0
	global_load_lds_dwordx4 v[178:179], off
	v_lshl_add_u64 v[178:179], v[234:235], 0, s[14:15]
	s_mov_b32 m0, s46
	s_nop 0
	global_load_lds_dwordx4 v[178:179], off
	v_lshl_add_u64 v[178:179], v[236:237], 0, s[14:15]
	s_mov_b32 m0, s47
	s_nop 0
	global_load_lds_dwordx4 v[178:179], off
	s_waitcnt vmcnt(8)
	s_waitcnt lgkmcnt(0)
	s_barrier
	s_setprio 1
	s_waitcnt lgkmcnt(0)
	v_mfma_f32_16x16x32_bf16 v[60:63], v[162:165], v[202:205], v[60:63]
	v_mfma_f32_16x16x32_bf16 v[56:59], v[170:173], v[202:205], v[56:59]
	v_mfma_f32_16x16x32_bf16 v[44:47], v[170:173], v[210:213], v[44:47]
	v_mfma_f32_16x16x32_bf16 v[52:55], v[162:165], v[210:213], v[52:55]
	v_mfma_f32_16x16x32_bf16 v[36:39], v[162:165], v[218:221], v[36:39]
	v_mfma_f32_16x16x32_bf16 v[32:35], v[170:173], v[218:221], v[32:35]
	v_mfma_f32_16x16x32_bf16 v[16:19], v[170:173], v[226:229], v[16:19]
	v_mfma_f32_16x16x32_bf16 v[20:23], v[162:165], v[226:229], v[20:23]
	v_mfma_f32_16x16x32_bf16 v[60:63], v[166:169], v[206:209], v[60:63]
	v_mfma_f32_16x16x32_bf16 v[56:59], v[174:177], v[206:209], v[56:59]
	v_mfma_f32_16x16x32_bf16 v[44:47], v[174:177], v[214:217], v[44:47]
	v_mfma_f32_16x16x32_bf16 v[52:55], v[166:169], v[214:217], v[52:55]
	v_mfma_f32_16x16x32_bf16 v[36:39], v[166:169], v[222:225], v[36:39]
	v_mfma_f32_16x16x32_bf16 v[32:35], v[174:177], v[222:225], v[32:35]
	v_mfma_f32_16x16x32_bf16 v[16:19], v[174:177], v[230:233], v[16:19]
	v_mfma_f32_16x16x32_bf16 v[20:23], v[166:169], v[230:233], v[20:23]
	s_setprio 0
	s_setprio 1
	v_mfma_f32_16x16x32_bf16 v[48:51], v[182:185], v[202:205], v[48:51]
	v_mfma_f32_16x16x32_bf16 v[40:43], v[194:197], v[202:205], v[40:43]
	v_mfma_f32_16x16x32_bf16 v[24:27], v[194:197], v[210:213], v[24:27]
	v_mfma_f32_16x16x32_bf16 v[28:31], v[182:185], v[210:213], v[28:31]
	v_mfma_f32_16x16x32_bf16 v[12:15], v[182:185], v[218:221], v[12:15]
	v_mfma_f32_16x16x32_bf16 v[8:11], v[194:197], v[218:221], v[8:11]
	v_mfma_f32_16x16x32_bf16 v[0:3], v[194:197], v[226:229], v[0:3]
	v_mfma_f32_16x16x32_bf16 v[4:7], v[182:185], v[226:229], v[4:7]
	v_mfma_f32_16x16x32_bf16 v[48:51], v[186:189], v[206:209], v[48:51]
	v_mfma_f32_16x16x32_bf16 v[40:43], v[198:201], v[206:209], v[40:43]
	v_mfma_f32_16x16x32_bf16 v[24:27], v[198:201], v[214:217], v[24:27]
	v_mfma_f32_16x16x32_bf16 v[28:31], v[186:189], v[214:217], v[28:31]
	v_mfma_f32_16x16x32_bf16 v[12:15], v[186:189], v[222:225], v[12:15]
	v_mfma_f32_16x16x32_bf16 v[8:11], v[198:201], v[222:225], v[8:11]
	v_mfma_f32_16x16x32_bf16 v[0:3], v[198:201], v[230:233], v[0:3]
	v_mfma_f32_16x16x32_bf16 v[4:7], v[186:189], v[230:233], v[4:7]
	s_setprio 0
	s_barrier
	s_add_i32 s52, s52, 2
	s_add_u32 s18, s18, 0x100
	s_addc_u32 s19, s19, 0
	s_cmp_gt_u32 s52, 13
	s_cbranch_scc0 .LBB0_586
	s_waitcnt vmcnt(0)
	s_cmpk_lt_u32 s33, 0x100
	s_cbranch_scc0 .LBB0_589
	s_barrier
